# prep: bf16(x) row loop issues its four loads together with counted waits
# speedup vs baseline: 1.0095x; 1.0039x over previous
.LBB0_162:
	v_ashrrev_i32_e32 v7, 31, v6
	s_waitcnt lgkmcnt(0)
	v_lshlrev_b64 v[16:17], 12, v[6:7]
	v_lshl_add_u64 v[28:29], v[4:5], 0, v[16:17]
	v_lshlrev_b64 v[20:21], 11, v[6:7]
	v_lshl_add_u64 v[32:33], v[0:1], 0, v[20:21]
	global_load_dwordx4 v[16:19], v[28:29], off
	global_load_dwordx4 v[20:23], v[28:29], off offset:1024
	global_load_dwordx4 v[24:27], v[28:29], off offset:2048
	global_load_dwordx4 v[28:31], v[28:29], off offset:3072
	s_waitcnt vmcnt(3)
	v_cvt_pk_bf16_f32 v48, v16, v17
	v_cvt_pk_bf16_f32 v49, v18, v19
	global_store_dwordx2 v[32:33], v[48:49], off
	s_waitcnt vmcnt(3)
	v_cvt_pk_bf16_f32 v50, v20, v21
	v_cvt_pk_bf16_f32 v51, v22, v23
	global_store_dwordx2 v[32:33], v[50:51], off offset:512
	s_waitcnt vmcnt(3)
	v_cvt_pk_bf16_f32 v52, v24, v25
	v_cvt_pk_bf16_f32 v53, v26, v27
	global_store_dwordx2 v[32:33], v[52:53], off offset:1024
	v_cmp_lt_i32_e64 s[0:1], v10, v9
	v_mul_f32_e32 v17, v17, v17
	v_mul_f32_e32 v19, v19, v19
	v_fmac_f32_e32 v17, v16, v16
	v_fmac_f32_e32 v19, v18, v18
	v_add_f32_e32 v16, v17, v19
	v_mul_f32_e32 v17, v21, v21
	v_mul_f32_e32 v18, v23, v23
	v_fmac_f32_e32 v17, v20, v20
	v_fmac_f32_e32 v18, v22, v22
	v_add_f32_e32 v17, v17, v18
	v_add_f32_e32 v16, v16, v17
	v_mul_f32_e32 v17, v25, v25
	v_mul_f32_e32 v18, v27, v27
	v_fmac_f32_e32 v17, v24, v24
	v_fmac_f32_e32 v18, v26, v26
	v_add_f32_e32 v17, v17, v18
	v_add_f32_e32 v16, v16, v17
	s_waitcnt vmcnt(3)
	v_mul_f32_e32 v17, v29, v29
	v_mul_f32_e32 v18, v31, v31
	v_fmac_f32_e32 v17, v28, v28
	v_fmac_f32_e32 v18, v30, v30
	v_cndmask_b32_e64 v34, v8, v10, s[0:1]
	v_add_f32_e32 v17, v17, v18
	v_lshlrev_b32_e32 v34, 2, v34
	v_add_f32_e32 v16, v16, v17
	ds_bpermute_b32 v17, v34, v16
	v_cmp_lt_i32_e64 s[0:1], v11, v9
	s_waitcnt lgkmcnt(0)
	v_add_f32_e32 v16, v16, v17
	v_cndmask_b32_e64 v18, v8, v11, s[0:1]
	v_lshlrev_b32_e32 v18, 2, v18
	ds_bpermute_b32 v17, v18, v16
	v_cmp_lt_i32_e64 s[0:1], v12, v9
	s_waitcnt lgkmcnt(0)
	v_add_f32_e32 v16, v16, v17
	v_cndmask_b32_e64 v18, v8, v12, s[0:1]
	v_lshlrev_b32_e32 v18, 2, v18
	ds_bpermute_b32 v17, v18, v16
	v_cmp_lt_i32_e64 s[0:1], v13, v9
	s_waitcnt lgkmcnt(0)
	v_add_f32_e32 v16, v16, v17
	v_cndmask_b32_e64 v18, v8, v13, s[0:1]
	v_lshlrev_b32_e32 v18, 2, v18
	ds_bpermute_b32 v17, v18, v16
	v_cmp_lt_i32_e64 s[0:1], v14, v9
	s_waitcnt lgkmcnt(0)
	v_add_f32_e32 v16, v16, v17
	v_cndmask_b32_e64 v18, v8, v14, s[0:1]
	v_lshlrev_b32_e32 v18, 2, v18
	ds_bpermute_b32 v17, v18, v16
	v_cmp_lt_i32_e64 s[0:1], v15, v9
	s_waitcnt lgkmcnt(0)
	v_add_f32_e32 v16, v16, v17
	v_cndmask_b32_e64 v18, v8, v15, s[0:1]
	v_lshlrev_b32_e32 v17, 2, v18
	ds_bpermute_b32 v17, v17, v16
	v_cvt_pk_bf16_f32 v18, v28, v29
	v_cvt_pk_bf16_f32 v19, v30, v31
	global_store_dwordx2 v[32:33], v[18:19], off offset:1536
	s_and_saveexec_b64 s[0:1], vcc
	s_cbranch_execz .LBB0_161
	s_waitcnt lgkmcnt(0)
	v_add_f32_e32 v16, v16, v17
	v_cndmask_b32_e64 v18, 0, v16, s[2:3]
	v_lshlrev_b64 v[16:17], 6, v[6:7]
	v_lshl_add_u64 v[16:17], v[2:3], 0, v[16:17]
	global_store_dword v[16:17], v18, off
	s_branch .LBB0_161
